# scan_post (both layers): the three row loads of a token are issued together instead of one per round trip
# speedup vs baseline: 1.1070x; 1.0037x over previous
; DI float silu_f(float x) { return x * __builtin_amdgcn_rcpf(1.f + __expf(-x)); }
; DI void scan_post(const P& p, int layer, int vb, int nvb) {
;     ...
;   for (int t = vb * 4 + wave; t < nrows; t += nvb * 4) {
;     float a[8], bb[8], gt[8];
;     unpack8(*(const uint4*)(o0 + (size_t)t * 512 + lane * 8), a);
;     unpack8(*(const uint4*)(o1 + (size_t)t * 512 + lane * 8), bb);
;     unpack8(*(const uint4*)(z + (size_t)t * ldz + goff + lane * 8), gt);
;     float ss = 0.f;
; #pragma unroll
;     for (int j = 0; j < 8; ++j) { a[j] += bb[j]; ss += a[j] * a[j]; }
;     ss += __shfl_xor(ss, 1); ss += __shfl_xor(ss, 2); ss += __shfl_xor(ss, 4);
;     float rms;
;     if (layer == 0) rms = rsqrtf(ss * (1.f / 64.f) + EPS);
;     else { ss += __shfl_xor(ss, 8); rms = rsqrtf(ss * (1.f / 128.f) + EPS); }
; #pragma unroll
;     for (int j = 0; j < 8; ++j) a[j] = a[j] * rms * on[j] * silu_f(gt[j]);
;     *(uint4*)(o0 + (size_t)t * 512 + lane * 8) = pack8(a);
.LBB0_822:
	v_lshl_add_u64 v[24:25], v[10:11], 0, v[8:9]
	v_add_co_u32_e32 v26, vcc, 0xf172000, v24
	v_add_u32_e32 v14, s16, v14
	s_nop 0
	v_addc_co_u32_e32 v27, vcc, 0, v25, vcc
	global_load_dwordx4 v[20:23], v[26:27], off
	v_add_co_u32_e32 v232, vcc, s49, v24
	s_nop 1
	v_addc_co_u32_e32 v233, vcc, 0, v25, vcc
	global_load_dwordx4 v[224:227], v[232:233], off
	v_lshl_add_u64 v[232:233], v[12:13], 0, v[8:9]
	global_load_dwordx4 v[228:231], v[232:233], off offset:-8
	v_lshl_add_u64 v[10:11], v[10:11], 0, s[38:39]
	s_waitcnt vmcnt(2)
	v_lshlrev_b32_e32 v28, 16, v20
	v_and_b32_e32 v29, 0xffff0000, v20
	v_lshlrev_b32_e32 v30, 16, v21
	v_and_b32_e32 v31, 0xffff0000, v21
	v_lshlrev_b32_e32 v32, 16, v22
	v_and_b32_e32 v33, 0xffff0000, v22
	v_lshlrev_b32_e32 v34, 16, v23
	v_and_b32_e32 v35, 0xffff0000, v23
	s_waitcnt vmcnt(1)
	v_lshlrev_b32_e32 v24, 16, v224
	v_and_b32_e32 v25, 0xffff0000, v224
	v_lshlrev_b32_e32 v36, 16, v225
	v_and_b32_e32 v37, 0xffff0000, v225
	v_lshlrev_b32_e32 v38, 16, v226
	v_and_b32_e32 v39, 0xffff0000, v226
	v_lshlrev_b32_e32 v40, 16, v227
	v_and_b32_e32 v41, 0xffff0000, v227
	v_pk_add_f32 v[24:25], v[28:29], v[24:25]
	v_pk_add_f32 v[30:31], v[30:31], v[36:37]
	v_pk_mul_f32 v[28:29], v[24:25], v[24:25]
	v_pk_mul_f32 v[36:37], v[30:31], v[30:31]
	v_pk_add_f32 v[32:33], v[32:33], v[38:39]
	v_pk_add_f32 v[34:35], v[34:35], v[40:41]
	v_pk_mul_f32 v[38:39], v[32:33], v[32:33]
	v_pk_mul_f32 v[40:41], v[34:35], v[34:35]
	v_lshl_add_u64 v[12:13], v[12:13], 0, s[18:19]
	s_waitcnt vmcnt(0)
	v_lshlrev_b32_e32 v44, 16, v230
	v_mul_f32_e32 v19, 0xbfb8aa3b, v44
	v_exp_f32_e32 v19, v19
	v_and_b32_e32 v45, 0xffff0000, v230
	v_lshlrev_b32_e32 v42, 16, v228
	v_and_b32_e32 v43, 0xffff0000, v228
	v_add_f32_e32 v19, 1.0, v19
	v_rcp_f32_e32 v46, v19
	v_mul_f32_e32 v19, 0xbfb8aa3b, v45
	v_exp_f32_e32 v19, v19
	v_lshlrev_b32_e32 v20, 16, v229
	v_and_b32_e32 v21, 0xffff0000, v229
	v_lshlrev_b32_e32 v22, 16, v231
	v_add_f32_e32 v19, 1.0, v19
	v_rcp_f32_e32 v47, v19
	v_mul_f32_e32 v19, 0xbfb8aa3b, v20
	v_exp_f32_e32 v19, v19
	v_and_b32_e32 v23, 0xffff0000, v231
	v_pk_mul_f32 v[44:45], v[46:47], v[44:45]
	v_add_f32_e32 v19, 1.0, v19
	v_rcp_f32_e32 v46, v19
	v_mul_f32_e32 v19, 0xbfb8aa3b, v21
	v_exp_f32_e32 v19, v19
	s_nop 0
	v_add_f32_e32 v19, 1.0, v19
	v_rcp_f32_e32 v47, v19
	v_mul_f32_e32 v19, 0xbfb8aa3b, v42
	v_exp_f32_e32 v19, v19
	v_pk_mul_f32 v[20:21], v[46:47], v[20:21]
	v_add_f32_e32 v19, 1.0, v19
	v_rcp_f32_e32 v46, v19
	v_mul_f32_e32 v19, 0xbfb8aa3b, v43
	v_exp_f32_e32 v19, v19
	s_nop 0
	v_add_f32_e32 v19, 1.0, v19
	v_rcp_f32_e32 v47, v19
	v_add_f32_e32 v19, v28, v29
	v_add_f32_e32 v19, v19, v36
	v_add_f32_e32 v19, v37, v19
	v_add_f32_e32 v19, v38, v19
	v_add_f32_e32 v19, v39, v19
	v_add_f32_e32 v19, v40, v19
	v_add_f32_e32 v19, v41, v19
	ds_bpermute_b32 v28, v15, v19
	v_pk_mul_f32 v[42:43], v[46:47], v[42:43]
	s_waitcnt lgkmcnt(0)
	v_add_f32_e32 v19, v19, v28
	ds_bpermute_b32 v28, v16, v19
	s_waitcnt lgkmcnt(0)
	v_add_f32_e32 v19, v19, v28
	ds_bpermute_b32 v28, v17, v19
	s_waitcnt lgkmcnt(0)
	v_add_f32_e32 v19, v19, v28
	ds_bpermute_b32 v28, v18, v19
	s_waitcnt lgkmcnt(0)
	v_add_f32_e32 v19, v19, v28
	v_fmamk_f32 v19, v19, 0x3c000000, v119
	v_cmp_gt_f32_e32 vcc, s9, v19
	v_mul_f32_e32 v28, 0x4b800000, v19
	s_nop 0
	v_cndmask_b32_e32 v19, v19, v28, vcc
	v_rsq_f32_e32 v19, v19
	s_nop 0
	v_mul_f32_e32 v28, 0x45800000, v19
	v_cndmask_b32_e32 v28, v19, v28, vcc
	v_mul_f32_e32 v19, 0xbfb8aa3b, v22
	v_exp_f32_e32 v19, v19
	v_pk_mul_f32 v[30:31], v[30:31], v[28:29] op_sel_hi:[1,0]
	v_pk_mul_f32 v[24:25], v[24:25], v[28:29] op_sel_hi:[1,0]
	v_pk_mul_f32 v[30:31], v[6:7], v[30:31]
	v_add_f32_e32 v19, 1.0, v19
	v_pk_mul_f32 v[30:31], v[20:21], v[30:31]
	v_pk_mul_f32 v[20:21], v[32:33], v[28:29] op_sel_hi:[1,0]
	v_pk_mul_f32 v[28:29], v[34:35], v[28:29] op_sel_hi:[1,0]
	v_pk_mul_f32 v[20:21], v[0:1], v[20:21]
	v_pk_mul_f32 v[24:25], v[4:5], v[24:25]
	v_pk_mul_f32 v[32:33], v[44:45], v[20:21]
	v_rcp_f32_e32 v20, v19
	v_mul_f32_e32 v19, 0xbfb8aa3b, v23
	v_exp_f32_e32 v19, v19
	v_pk_mul_f32 v[28:29], v[2:3], v[28:29]
	v_pk_mul_f32 v[24:25], v[42:43], v[24:25]
	v_cmp_lt_i32_e32 vcc, s46, v14
	v_add_f32_e32 v19, 1.0, v19
	v_rcp_f32_e32 v21, v19
	s_or_b64 s[4:5], vcc, s[4:5]
	v_pk_mul_f32 v[20:21], v[20:21], v[22:23]
	s_nop 0
	v_pk_mul_f32 v[28:29], v[20:21], v[28:29]
	v_cvt_pk_bf16_f32 v20, v24, v25
	v_cvt_pk_bf16_f32 v21, v30, v31
	v_cvt_pk_bf16_f32 v22, v32, v33
	v_cvt_pk_bf16_f32 v23, v28, v29
	global_store_dwordx4 v[26:27], v[20:23], off
	s_andn2_b64 exec, exec, s[4:5]
	s_cbranch_execnz .LBB0_822

; DI float silu_f(float x) { return x * __builtin_amdgcn_rcpf(1.f + __expf(-x)); }
; DI void scan_post(const P& p, int layer, int vb, int nvb) {
;     ...
;   for (int t = vb * 4 + wave; t < nrows; t += nvb * 4) {
;     float a[8], bb[8], gt[8];
;     unpack8(*(const uint4*)(o0 + (size_t)t * 512 + lane * 8), a);
;     unpack8(*(const uint4*)(o1 + (size_t)t * 512 + lane * 8), bb);
;     unpack8(*(const uint4*)(z + (size_t)t * ldz + goff + lane * 8), gt);
;     float ss = 0.f;
; #pragma unroll
;     for (int j = 0; j < 8; ++j) { a[j] += bb[j]; ss += a[j] * a[j]; }
;     ss += __shfl_xor(ss, 1); ss += __shfl_xor(ss, 2); ss += __shfl_xor(ss, 4);
;     float rms;
;     if (layer == 0) rms = rsqrtf(ss * (1.f / 64.f) + EPS);
;     else { ss += __shfl_xor(ss, 8); rms = rsqrtf(ss * (1.f / 128.f) + EPS); }
; #pragma unroll
;     for (int j = 0; j < 8; ++j) a[j] = a[j] * rms * on[j] * silu_f(gt[j]);
;     *(uint4*)(o0 + (size_t)t * 512 + lane * 8) = pack8(a);
.LBB0_1236:
	v_lshl_add_u64 v[22:23], v[10:11], 0, v[8:9]
	v_add_co_u32_e32 v24, vcc, 0xf172000, v22
	v_add_u32_e32 v14, s16, v14
	s_nop 0
	v_addc_co_u32_e32 v25, vcc, 0, v23, vcc
	global_load_dwordx4 v[18:21], v[24:25], off
	v_add_co_u32_e32 v232, vcc, s15, v22
	s_nop 1
	v_addc_co_u32_e32 v233, vcc, 0, v23, vcc
	global_load_dwordx4 v[224:227], v[232:233], off
	v_lshl_add_u64 v[232:233], v[12:13], 0, v[8:9]
	global_load_dwordx4 v[228:231], v[232:233], off offset:-8
	v_lshl_add_u64 v[10:11], v[10:11], 0, s[18:19]
	s_waitcnt vmcnt(2)
	v_lshlrev_b32_e32 v26, 16, v18
	v_and_b32_e32 v27, 0xffff0000, v18
	v_lshlrev_b32_e32 v28, 16, v19
	v_and_b32_e32 v29, 0xffff0000, v19
	v_lshlrev_b32_e32 v30, 16, v20
	v_and_b32_e32 v31, 0xffff0000, v20
	v_lshlrev_b32_e32 v32, 16, v21
	v_and_b32_e32 v33, 0xffff0000, v21
	s_waitcnt vmcnt(1)
	v_lshlrev_b32_e32 v22, 16, v224
	v_and_b32_e32 v23, 0xffff0000, v224
	v_lshlrev_b32_e32 v34, 16, v225
	v_and_b32_e32 v35, 0xffff0000, v225
	v_lshlrev_b32_e32 v36, 16, v226
	v_and_b32_e32 v37, 0xffff0000, v226
	v_lshlrev_b32_e32 v38, 16, v227
	v_and_b32_e32 v39, 0xffff0000, v227
	v_pk_add_f32 v[22:23], v[26:27], v[22:23]
	v_pk_add_f32 v[28:29], v[28:29], v[34:35]
	v_pk_mul_f32 v[26:27], v[22:23], v[22:23]
	v_pk_mul_f32 v[34:35], v[28:29], v[28:29]
	v_add_f32_e32 v26, v26, v27
	v_pk_add_f32 v[30:31], v[30:31], v[36:37]
	v_add_f32_e32 v26, v26, v34
	v_pk_mul_f32 v[36:37], v[30:31], v[30:31]
	v_add_f32_e32 v26, v35, v26
	v_pk_add_f32 v[32:33], v[32:33], v[38:39]
	v_add_f32_e32 v26, v36, v26
	v_pk_mul_f32 v[38:39], v[32:33], v[32:33]
	v_add_f32_e32 v26, v37, v26
	v_add_f32_e32 v26, v38, v26
	v_add_f32_e32 v26, v39, v26
	ds_bpermute_b32 v27, v15, v26
	v_lshl_add_u64 v[12:13], v[12:13], 0, s[38:39]
	s_waitcnt lgkmcnt(0)
	v_add_f32_e32 v26, v26, v27
	ds_bpermute_b32 v27, v16, v26
	s_waitcnt lgkmcnt(0)
	v_add_f32_e32 v26, v26, v27
	ds_bpermute_b32 v27, v17, v26
	s_waitcnt lgkmcnt(0)
	v_add_f32_e32 v26, v26, v27
	v_fmamk_f32 v26, v26, 0x3c800000, v119
	v_cmp_gt_f32_e32 vcc, s9, v26
	v_mul_f32_e32 v27, 0x4b800000, v26
	s_waitcnt vmcnt(0)
	v_lshlrev_b32_e32 v42, 16, v230
	v_and_b32_e32 v43, 0xffff0000, v230
	v_mul_f32_e32 v44, 0xbfb8aa3b, v42
	v_mul_f32_e32 v45, 0xbfb8aa3b, v43
	v_exp_f32_e32 v44, v44
	v_exp_f32_e32 v45, v45
	v_lshlrev_b32_e32 v40, 16, v228
	v_and_b32_e32 v41, 0xffff0000, v228
	v_add_f32_e32 v44, 1.0, v44
	v_add_f32_e32 v45, 1.0, v45
	v_rcp_f32_e32 v44, v44
	v_rcp_f32_e32 v45, v45
	v_lshlrev_b32_e32 v18, 16, v229
	v_and_b32_e32 v19, 0xffff0000, v229
	v_cndmask_b32_e32 v26, v26, v27, vcc
	v_pk_mul_f32 v[42:43], v[44:45], v[42:43]
	v_mul_f32_e32 v44, 0xbfb8aa3b, v18
	v_mul_f32_e32 v45, 0xbfb8aa3b, v19
	v_exp_f32_e32 v44, v44
	v_exp_f32_e32 v45, v45
	v_rsq_f32_e32 v26, v26
	v_lshlrev_b32_e32 v20, 16, v231
	v_add_f32_e32 v44, 1.0, v44
	v_add_f32_e32 v45, 1.0, v45
	v_rcp_f32_e32 v44, v44
	v_rcp_f32_e32 v45, v45
	v_mul_f32_e32 v27, 0x45800000, v26
	v_cndmask_b32_e32 v26, v26, v27, vcc
	v_pk_mul_f32 v[28:29], v[28:29], v[26:27] op_sel_hi:[1,0]
	v_pk_mul_f32 v[18:19], v[44:45], v[18:19]
	v_pk_mul_f32 v[28:29], v[6:7], v[28:29]
	v_and_b32_e32 v21, 0xffff0000, v231
	v_pk_mul_f32 v[28:29], v[18:19], v[28:29]
	v_pk_mul_f32 v[18:19], v[30:31], v[26:27] op_sel_hi:[1,0]
	v_mul_f32_e32 v44, 0xbfb8aa3b, v40
	v_pk_mul_f32 v[18:19], v[0:1], v[18:19]
	v_mul_f32_e32 v45, 0xbfb8aa3b, v41
	v_pk_mul_f32 v[30:31], v[42:43], v[18:19]
	v_mul_f32_e32 v18, 0xbfb8aa3b, v20
	v_mul_f32_e32 v19, 0xbfb8aa3b, v21
	v_exp_f32_e32 v44, v44
	v_exp_f32_e32 v45, v45
	v_exp_f32_e32 v18, v18
	v_exp_f32_e32 v19, v19
	v_add_f32_e32 v44, 1.0, v44
	v_add_f32_e32 v45, 1.0, v45
	v_add_f32_e32 v18, 1.0, v18
	v_add_f32_e32 v19, 1.0, v19
	v_rcp_f32_e32 v44, v44
	v_rcp_f32_e32 v45, v45
	v_rcp_f32_e32 v18, v18
	v_rcp_f32_e32 v19, v19
	v_pk_mul_f32 v[22:23], v[22:23], v[26:27] op_sel_hi:[1,0]
	v_pk_mul_f32 v[26:27], v[32:33], v[26:27] op_sel_hi:[1,0]
	v_pk_mul_f32 v[40:41], v[44:45], v[40:41]
	v_pk_mul_f32 v[22:23], v[4:5], v[22:23]
	v_pk_mul_f32 v[26:27], v[2:3], v[26:27]
	v_pk_mul_f32 v[18:19], v[18:19], v[20:21]
	v_pk_mul_f32 v[22:23], v[40:41], v[22:23]
	v_pk_mul_f32 v[26:27], v[18:19], v[26:27]
	v_cmp_lt_i32_e32 vcc, s48, v14
	v_cvt_pk_bf16_f32 v18, v22, v23
	v_cvt_pk_bf16_f32 v19, v28, v29
	v_cvt_pk_bf16_f32 v20, v30, v31
	v_cvt_pk_bf16_f32 v21, v26, v27
	s_or_b64 s[4:5], vcc, s[4:5]
	global_store_dwordx4 v[24:25], v[18:21], off
	s_andn2_b64 exec, exec, s[4:5]
	s_cbranch_execnz .LBB0_1236
